# LN row loops: x base pointer scalar load hoisted out of the per-row loop
# baseline (speedup 1.0000x reference)
.LBB0_997:
	s_or_b64 exec, exec, s[2:3]
	v_readlane_b32 s6, v255, 2
	v_readlane_b32 s7, v255, 3
	s_waitcnt lgkmcnt(0)
	v_mov_b32_e32 v0, v190
	v_mov_b32_e32 v1, v190
	s_barrier
	s_mov_b32 s0, s94
	v_ashrrev_i32_e32 v1, 6, v1
	s_lshl_b32 s64, s26, 10
	v_lshl_add_u32 v16, s0, 3, v1
	s_movk_i32 s0, 0x4200
	s_mov_b32 s65, s55
	v_cmp_gt_i32_e32 vcc, s0, v16
	s_and_saveexec_b64 s[8:9], vcc
	s_cbranch_execz .LBB0_1008
	s_load_dwordx2 s[4:5], s[6:7], 0xf0
	s_load_dwordx2 s[20:21], s[6:7], 0xe8
	v_readlane_b32 s10, v255, 2
	v_readlane_b32 s11, v255, 3
	s_load_dwordx4 s[0:3], s[10:11], 0xa8
	v_and_b32_e32 v1, 63, v0
	s_waitcnt lgkmcnt(0)
	s_add_u32 s10, s4, s62
	s_addc_u32 s11, s5, s63
	s_add_u32 s10, s10, 0x3180000
	s_addc_u32 s11, s11, 0
	s_lshl_b64 s[12:13], s[64:65], 2
	s_add_u32 s2, s2, s12
	s_addc_u32 s3, s3, s13
	s_add_u32 s0, s0, s12
	s_addc_u32 s1, s1, s13
	s_add_u32 s12, s4, 0x31aa000
	v_lshlrev_b32_e32 v176, 4, v1
	v_lshlrev_b32_e32 v18, 2, v1
	s_addc_u32 s13, s5, 0
	v_lshl_add_u64 v[20:21], s[0:1], 0, v[176:177]
	v_lshl_add_u64 v[22:23], s[2:3], 0, v[176:177]
	global_load_dwordx4 v[140:143], v[20:21], off
	global_load_dwordx4 v[144:147], v[22:23], off
	global_load_dwordx4 v[148:151], v[20:21], off offset:1024
	global_load_dwordx4 v[152:155], v[22:23], off offset:1024
	global_load_dwordx4 v[156:159], v[20:21], off offset:2048
	global_load_dwordx4 v[160:163], v[22:23], off offset:2048
	global_load_dwordx4 v[164:167], v[20:21], off offset:3072
	global_load_dwordx4 v[168:171], v[22:23], off offset:3072
	v_lshlrev_b32_e32 v176, 3, v1
	s_add_u32 s14, s4, 0xf37e000
	v_or_b32_e32 v0, 0x100, v18
	v_or_b32_e32 v2, 0x200, v18
	v_or_b32_e32 v4, 0x300, v18
	v_lshl_add_u64 v[6:7], s[4:5], 0, v[176:177]
	s_mov_b64 s[0:1], 0x33aa000
	v_cmp_eq_u32_e32 vcc, 0, v1
	s_addc_u32 s15, s5, 0
	v_lshl_add_u64 v[24:25], v[6:7], 0, s[0:1]
	s_mov_b64 s[16:17], 0
	v_lshlrev_b32_e32 v26, 2, v0
	v_lshlrev_b32_e32 v28, 2, v2
	v_lshlrev_b32_e32 v30, 2, v4
	s_branch .LBB0_1001

.LBB0_1001:
	v_mul_hi_i32 v0, v16, s35
	v_lshrrev_b32_e32 v1, 31, v0
	v_ashrrev_i32_e32 v0, 11, v0
	v_add_u32_e32 v19, v0, v1
	v_mad_i32_i24 v1, v19, s33, v16
	v_cmp_gt_i32_e64 s[2:3], s95, v1
	s_and_b64 s[0:1], s[56:57], s[2:3]
	v_cmp_lt_i32_e64 s[4:5], s82, v1
	s_xor_b64 s[0:1], s[0:1], -1
	s_and_saveexec_b64 s[18:19], s[0:1]
	s_cbranch_execz .LBB0_1000
	s_and_saveexec_b64 s[0:1], s[4:5]
	s_xor_b64 s[0:1], exec, s[0:1]
	v_mul_i32_i24_e32 v0, 0xffffdf00, v19
	v_lshl_add_u32 v0, v19, 13, v0
	v_add3_u32 v0, v16, v0, s79
	s_or_saveexec_b64 s[0:1], s[0:1]
	s_waitcnt lgkmcnt(0)
	v_mov_b64_e32 v[2:3], s[20:21]
	s_xor_b64 exec, exec, s[0:1]
	v_lshl_add_u32 v0, v19, 8, v1
	v_mov_b64_e32 v[2:3], s[12:13]
	s_or_b64 exec, exec, s[0:1]
	v_ashrrev_i32_e32 v1, 31, v0
	v_lshlrev_b64 v[0:1], 12, v[0:1]
	v_lshl_add_u64 v[0:1], v[2:3], 0, v[0:1]
	v_lshlrev_b32_e32 v176, 2, v18
	v_lshl_add_u64 v[32:33], v[0:1], 0, v[176:177]
	global_load_dwordx4 v[12:15], v[32:33], off
	global_load_dwordx4 v[8:11], v[32:33], off offset:1024
	global_load_dwordx4 v[4:7], v[32:33], off offset:2048
	global_load_dwordx4 v[0:3], v[32:33], off offset:3072
	v_and_b32_e32 v27, 64, v196
	v_add_u32_e32 v27, 64, v27
	v_xor_b32_e32 v29, 32, v196
	v_cmp_lt_i32_e64 s[4:5], v29, v27
	s_mov_b32 s0, 0x800000
	s_waitcnt vmcnt(3)
	v_mov_b32_e32 v34, v13
	v_mov_b32_e32 v35, v14
	v_mov_b32_e32 v36, v12
	v_mov_b32_e32 v37, v15
	v_pk_add_f32 v[34:35], v[34:35], v[36:37]
	s_waitcnt vmcnt(2)
	v_mov_b32_e32 v36, v9
	v_mov_b32_e32 v37, v10
	v_mov_b32_e32 v38, v8
	v_mov_b32_e32 v39, v11
	v_pk_add_f32 v[36:37], v[36:37], v[38:39]
	v_add_f32_e32 v17, v34, v35
	v_pk_add_f32 v[36:37], v[36:37], v[36:37] op_sel:[0,1] op_sel_hi:[1,0]
	v_add_f32_e32 v34, 0, v17
	s_waitcnt vmcnt(1)
	v_add_f32_e32 v38, v4, v5
	v_add_f32_e32 v40, v6, v7
	s_waitcnt vmcnt(0)
	v_mov_b32_e32 v35, v0
	v_mov_b32_e32 v37, v1
	v_mov_b32_e32 v39, v2
	v_mov_b32_e32 v41, v3
	v_pk_add_f32 v[34:35], v[34:35], v[36:37]
	v_pk_add_f32 v[36:37], v[38:39], v[40:41]
	v_cndmask_b32_e64 v29, v196, v29, s[4:5]
	v_pk_add_f32 v[34:35], v[34:35], v[36:37]
	v_lshlrev_b32_e32 v29, 2, v29
	v_add_f32_e32 v17, v34, v35
	ds_bpermute_b32 v31, v29, v17
	s_waitcnt lgkmcnt(0)
	v_add_f32_e32 v17, v17, v31
	v_xor_b32_e32 v31, 16, v196
	v_cmp_lt_i32_e64 s[4:5], v31, v27
	s_nop 1
	v_cndmask_b32_e64 v31, v196, v31, s[4:5]
	v_lshlrev_b32_e32 v31, 2, v31
	ds_bpermute_b32 v34, v31, v17
	s_waitcnt lgkmcnt(0)
	v_add_f32_e32 v17, v17, v34
	v_xor_b32_e32 v34, 8, v196
	v_cmp_lt_i32_e64 s[4:5], v34, v27
	s_nop 1
	v_cndmask_b32_e64 v34, v196, v34, s[4:5]
	v_lshlrev_b32_e32 v42, 2, v34
	ds_bpermute_b32 v34, v42, v17
	s_waitcnt lgkmcnt(0)
	v_add_f32_e32 v17, v17, v34
	v_xor_b32_e32 v34, 4, v196
	v_cmp_lt_i32_e64 s[4:5], v34, v27
	s_nop 1
	v_cndmask_b32_e64 v34, v196, v34, s[4:5]
	v_lshlrev_b32_e32 v43, 2, v34
	ds_bpermute_b32 v34, v43, v17
	s_waitcnt lgkmcnt(0)
	v_add_f32_e32 v17, v17, v34
	v_xor_b32_e32 v34, 2, v196
	v_cmp_lt_i32_e64 s[4:5], v34, v27
	s_nop 1
	v_cndmask_b32_e64 v34, v196, v34, s[4:5]
	v_lshlrev_b32_e32 v44, 2, v34
	ds_bpermute_b32 v34, v44, v17
	s_waitcnt lgkmcnt(0)
	v_add_f32_e32 v17, v17, v34
	v_xor_b32_e32 v34, 1, v196
	v_cmp_lt_i32_e64 s[4:5], v34, v27
	s_nop 1
	v_cndmask_b32_e64 v27, v196, v34, s[4:5]
	v_lshlrev_b32_e32 v27, 2, v27
	ds_bpermute_b32 v34, v27, v17
	s_waitcnt lgkmcnt(0)
	v_add_f32_e32 v17, v17, v34
	v_fmamk_f32 v13, v17, 0xba800000, v13
	v_fmamk_f32 v12, v17, 0xba800000, v12
	v_fmamk_f32 v15, v17, 0xba800000, v15
	v_fmac_f32_e32 v14, 0xba800000, v17
	v_pk_mul_f32 v[34:35], v[14:15], v[14:15]
	v_pk_mul_f32 v[36:37], v[12:13], v[12:13]
	v_fmamk_f32 v9, v17, 0xba800000, v9
	v_pk_mov_b32 v[38:39], v[36:37], v[34:35] op_sel:[1,0]
	v_mov_b32_e32 v37, v35
	v_pk_add_f32 v[34:35], v[38:39], v[36:37]
	v_fmamk_f32 v8, v17, 0xba800000, v8
	v_fmamk_f32 v11, v17, 0xba800000, v11
	v_fmac_f32_e32 v10, 0xba800000, v17
	v_pk_add_f32 v[34:35], v[34:35], v[34:35] op_sel_hi:[0,1]
	v_pk_mul_f32 v[36:37], v[10:11], v[10:11]
	v_pk_mul_f32 v[38:39], v[8:9], v[8:9]
	v_fmamk_f32 v4, v17, 0xba800000, v4
	v_pk_mov_b32 v[40:41], v[38:39], v[36:37] op_sel:[1,0]
	v_mov_b32_e32 v39, v37
	v_fmamk_f32 v5, v17, 0xba800000, v5
	v_fmac_f32_e32 v6, 0xba800000, v17
	v_mul_f32_e32 v34, v4, v4
	v_pk_add_f32 v[36:37], v[40:41], v[38:39]
	v_fmamk_f32 v7, v17, 0xba800000, v7
	v_pk_fma_f32 v[38:39], v[4:5], v[4:5], v[34:35] op_sel_hi:[1,1,0]
	v_mul_f32_e32 v34, v6, v6
	v_pk_add_f32 v[36:37], v[36:37], v[36:37] op_sel_hi:[0,1]
	v_pk_fma_f32 v[40:41], v[6:7], v[6:7], v[34:35] op_sel_hi:[1,1,0]
	v_fmamk_f32 v3, v17, 0xba800000, v3
	v_fmamk_f32 v2, v17, 0xba800000, v2
	v_fmamk_f32 v1, v17, 0xba800000, v1
	v_fmac_f32_e32 v0, 0xba800000, v17
	v_mul_f32_e32 v38, v0, v0
	v_mul_f32_e32 v40, v1, v1
	v_mul_f32_e32 v34, v2, v2
	v_mul_f32_e32 v36, v3, v3
	v_pk_add_f32 v[38:39], v[38:39], v[40:41]
	v_pk_add_f32 v[34:35], v[34:35], v[36:37]
	s_nop 0
	v_pk_add_f32 v[34:35], v[38:39], v[34:35]
	s_nop 0
	v_add_f32_e32 v17, v34, v35
	ds_bpermute_b32 v29, v29, v17
	s_waitcnt lgkmcnt(0)
	v_add_f32_e32 v17, v17, v29
	ds_bpermute_b32 v29, v31, v17
	s_waitcnt lgkmcnt(0)
	v_add_f32_e32 v17, v17, v29
	ds_bpermute_b32 v29, v42, v17
	s_waitcnt lgkmcnt(0)
	v_add_f32_e32 v17, v17, v29
	ds_bpermute_b32 v29, v43, v17
	s_waitcnt lgkmcnt(0)
	v_add_f32_e32 v17, v17, v29
	ds_bpermute_b32 v29, v44, v17
	s_waitcnt lgkmcnt(0)
	v_add_f32_e32 v17, v17, v29
	ds_bpermute_b32 v27, v27, v17
	s_waitcnt lgkmcnt(0)
	v_add_f32_e32 v17, v17, v27
	v_fmamk_f32 v17, v17, 0x3a800000, v197
	v_cmp_gt_f32_e64 s[4:5], s0, v17
	v_mul_f32_e32 v27, 0x4b800000, v17
	s_nop 0
	v_cndmask_b32_e64 v17, v17, v27, s[4:5]
	v_rsq_f32_e32 v17, v17
	s_nop 0
	v_mul_f32_e32 v27, 0x45800000, v17
	v_cndmask_b32_e64 v34, v17, v27, s[4:5]
	v_pk_mul_f32 v[44:45], v[12:13], v[34:35] op_sel_hi:[1,0]
	v_pk_mul_f32 v[12:13], v[14:15], v[34:35] op_sel_hi:[1,0]
	s_and_b64 s[4:5], s[2:3], s[60:61]
	v_ashrrev_i32_e32 v17, 31, v16
	v_pk_fma_f32 v[12:13], v[142:143], v[12:13], v[146:147]
	v_pk_fma_f32 v[14:15], v[140:141], v[44:45], v[144:145]
	v_pk_mul_f32 v[44:45], v[8:9], v[34:35] op_sel_hi:[1,0]
	v_pk_mul_f32 v[8:9], v[10:11], v[34:35] op_sel_hi:[1,0]
	v_pk_fma_f32 v[10:11], v[148:149], v[44:45], v[152:153]
	v_pk_fma_f32 v[8:9], v[150:151], v[8:9], v[154:155]
	v_pk_mul_f32 v[44:45], v[4:5], v[34:35] op_sel_hi:[1,0]
	v_pk_mul_f32 v[4:5], v[6:7], v[34:35] op_sel_hi:[1,0]
	v_pk_fma_f32 v[6:7], v[156:157], v[44:45], v[160:161]
	v_pk_fma_f32 v[4:5], v[158:159], v[4:5], v[162:163]
	v_pk_mul_f32 v[44:45], v[0:1], v[34:35] op_sel_hi:[1,0]
	v_pk_mul_f32 v[0:1], v[2:3], v[34:35] op_sel_hi:[1,0]
	v_pk_fma_f32 v[2:3], v[164:165], v[44:45], v[168:169]
	v_pk_fma_f32 v[0:1], v[166:167], v[0:1], v[170:171]
	v_cndmask_b32_e64 v38, 1.0, v252, s[4:5]
	v_pk_mul_f32 v[36:37], v[38:39], v[12:13] op_sel_hi:[0,1]
	v_pk_mul_f32 v[34:35], v[38:39], v[14:15] op_sel_hi:[0,1]
	global_store_dwordx4 v[32:33], v[34:37], off
	s_nop 1
	v_pk_mul_f32 v[36:37], v[38:39], v[8:9] op_sel_hi:[0,1]
	v_pk_mul_f32 v[34:35], v[38:39], v[10:11] op_sel_hi:[0,1]
	global_store_dwordx4 v[32:33], v[34:37], off offset:1024
	s_nop 1
	v_pk_mul_f32 v[36:37], v[38:39], v[4:5] op_sel_hi:[0,1]
	v_pk_mul_f32 v[34:35], v[38:39], v[6:7] op_sel_hi:[0,1]
	global_store_dwordx4 v[32:33], v[34:37], off offset:2048
	s_nop 1
	v_pk_mul_f32 v[36:37], v[38:39], v[0:1] op_sel_hi:[0,1]
	v_pk_mul_f32 v[34:35], v[38:39], v[2:3] op_sel_hi:[0,1]
	global_store_dwordx4 v[32:33], v[34:37], off offset:3072
	s_and_saveexec_b64 s[0:1], vcc
	s_cbranch_execz .LBB0_999
	v_mov_b32_e32 v34, v177
	v_lshl_add_u64 v[32:33], v[16:17], 3, s[14:15]
	s_nop 0
	v_mov_b32_e32 v35, v34
	global_store_dwordx2 v[32:33], v[34:35], off
	s_branch .LBB0_999

.LBB0_1483:
	s_or_b64 exec, exec, s[0:1]
	v_readlane_b32 s0, v255, 2
	v_readlane_b32 s1, v255, 3
	s_waitcnt lgkmcnt(0)
	v_mov_b32_e32 v0, v190
	v_mov_b32_e32 v1, v190
	s_barrier
	s_mov_b32 s2, s94
	v_ashrrev_i32_e32 v1, 6, v1
	s_nop 0
	v_lshl_add_u32 v16, s2, 3, v1
	s_movk_i32 s2, 0x4200
	v_cmp_gt_i32_e32 vcc, s2, v16
	s_and_saveexec_b64 s[6:7], vcc
	s_cbranch_execz .LBB0_1495
	s_load_dwordx2 s[4:5], s[0:1], 0xf0
	s_load_dwordx2 s[20:21], s[0:1], 0xe8
	v_readlane_b32 s2, v255, 2
	v_readlane_b32 s3, v255, 3
	s_load_dwordx4 s[12:15], s[2:3], 0xd8
	v_and_b32_e32 v1, 63, v0
	s_waitcnt lgkmcnt(0)
	s_add_u32 s2, s4, s62
	s_addc_u32 s3, s5, s63
	s_add_u32 s8, s2, 0x3192000
	s_addc_u32 s9, s3, 0
	s_lshl_b64 s[2:3], s[64:65], 2
	s_add_u32 s14, s14, s2
	s_addc_u32 s15, s15, s3
	s_add_u32 s16, s12, s2
	s_addc_u32 s17, s13, s3
	s_add_u32 s10, s4, 0x31aa000
	s_addc_u32 s11, s5, 0
	v_lshlrev_b32_e32 v176, 4, v1
	v_lshlrev_b32_e32 v18, 2, v1
	s_add_u32 s12, s4, 0xf37e000
	v_lshl_add_u64 v[20:21], s[16:17], 0, v[176:177]
	v_lshl_add_u64 v[22:23], s[14:15], 0, v[176:177]
	global_load_dwordx4 v[140:143], v[20:21], off
	global_load_dwordx4 v[144:147], v[22:23], off
	global_load_dwordx4 v[148:151], v[20:21], off offset:1024
	global_load_dwordx4 v[152:155], v[22:23], off offset:1024
	global_load_dwordx4 v[156:159], v[20:21], off offset:2048
	global_load_dwordx4 v[160:163], v[22:23], off offset:2048
	global_load_dwordx4 v[164:167], v[20:21], off offset:3072
	global_load_dwordx4 v[168:171], v[22:23], off offset:3072
	v_lshlrev_b32_e32 v176, 3, v1
	s_addc_u32 s13, s5, 0
	v_or_b32_e32 v0, 0x100, v18
	v_or_b32_e32 v2, 0x200, v18
	v_or_b32_e32 v4, 0x300, v18
	v_lshl_add_u64 v[6:7], s[4:5], 0, v[176:177]
	s_mov_b64 s[4:5], 0x33aa000
	v_cmp_eq_u32_e64 s[2:3], 0, v1
	v_lshl_add_u64 v[24:25], v[6:7], 0, s[4:5]
	s_mov_b64 s[14:15], 0
	v_lshlrev_b32_e32 v26, 2, v0
	v_lshlrev_b32_e32 v28, 2, v2
	v_lshlrev_b32_e32 v30, 2, v4
	s_branch .LBB0_1487

.LBB0_1487:
	v_mul_hi_i32 v0, v16, s35
	v_lshrrev_b32_e32 v1, 31, v0
	v_ashrrev_i32_e32 v0, 11, v0
	v_add_u32_e32 v19, v0, v1
	v_mad_i32_i24 v1, v19, s33, v16
	v_cmp_gt_i32_e64 s[4:5], s95, v1
	s_and_b64 s[16:17], s[56:57], s[4:5]
	v_cmp_lt_i32_e32 vcc, s82, v1
	s_xor_b64 s[18:19], s[16:17], -1
	s_and_saveexec_b64 s[16:17], s[18:19]
	s_cbranch_execz .LBB0_1486
	s_and_saveexec_b64 s[18:19], vcc
	s_xor_b64 s[18:19], exec, s[18:19]
	v_mul_i32_i24_e32 v0, 0xffffdf00, v19
	v_lshl_add_u32 v0, v19, 13, v0
	v_add3_u32 v0, v16, v0, s79
	s_or_saveexec_b64 s[18:19], s[18:19]
	s_waitcnt lgkmcnt(0)
	v_mov_b64_e32 v[2:3], s[20:21]
	s_xor_b64 exec, exec, s[18:19]
	v_lshl_add_u32 v0, v19, 8, v1
	v_mov_b64_e32 v[2:3], s[10:11]
	s_or_b64 exec, exec, s[18:19]
	v_ashrrev_i32_e32 v1, 31, v0
	v_lshlrev_b64 v[0:1], 12, v[0:1]
	v_lshl_add_u64 v[0:1], v[2:3], 0, v[0:1]
	v_lshlrev_b32_e32 v176, 2, v18
	v_lshl_add_u64 v[32:33], v[0:1], 0, v[176:177]
	global_load_dwordx4 v[12:15], v[32:33], off
	global_load_dwordx4 v[8:11], v[32:33], off offset:1024
	global_load_dwordx4 v[4:7], v[32:33], off offset:2048
	global_load_dwordx4 v[0:3], v[32:33], off offset:3072
	v_and_b32_e32 v27, 64, v196
	v_add_u32_e32 v27, 64, v27
	v_xor_b32_e32 v29, 32, v196
	v_cmp_lt_i32_e32 vcc, v29, v27
	s_mov_b32 s18, 0x800000
	s_waitcnt vmcnt(3)
	v_mov_b32_e32 v34, v13
	v_mov_b32_e32 v35, v14
	v_mov_b32_e32 v36, v12
	v_mov_b32_e32 v37, v15
	v_pk_add_f32 v[34:35], v[34:35], v[36:37]
	s_waitcnt vmcnt(2)
	v_mov_b32_e32 v36, v9
	v_mov_b32_e32 v37, v10
	v_mov_b32_e32 v38, v8
	v_mov_b32_e32 v39, v11
	v_pk_add_f32 v[36:37], v[36:37], v[38:39]
	v_add_f32_e32 v17, v34, v35
	v_pk_add_f32 v[36:37], v[36:37], v[36:37] op_sel:[0,1] op_sel_hi:[1,0]
	v_add_f32_e32 v34, 0, v17
	s_waitcnt vmcnt(1)
	v_add_f32_e32 v38, v4, v5
	v_add_f32_e32 v40, v6, v7
	s_waitcnt vmcnt(0)
	v_mov_b32_e32 v35, v0
	v_mov_b32_e32 v37, v1
	v_mov_b32_e32 v39, v2
	v_mov_b32_e32 v41, v3
	v_pk_add_f32 v[34:35], v[34:35], v[36:37]
	v_pk_add_f32 v[36:37], v[38:39], v[40:41]
	v_cndmask_b32_e32 v29, v196, v29, vcc
	v_pk_add_f32 v[34:35], v[34:35], v[36:37]
	v_lshlrev_b32_e32 v29, 2, v29
	v_add_f32_e32 v17, v34, v35
	ds_bpermute_b32 v31, v29, v17
	s_waitcnt lgkmcnt(0)
	v_add_f32_e32 v17, v17, v31
	v_xor_b32_e32 v31, 16, v196
	v_cmp_lt_i32_e32 vcc, v31, v27
	s_nop 1
	v_cndmask_b32_e32 v31, v196, v31, vcc
	v_lshlrev_b32_e32 v31, 2, v31
	ds_bpermute_b32 v34, v31, v17
	s_waitcnt lgkmcnt(0)
	v_add_f32_e32 v17, v17, v34
	v_xor_b32_e32 v34, 8, v196
	v_cmp_lt_i32_e32 vcc, v34, v27
	s_nop 1
	v_cndmask_b32_e32 v34, v196, v34, vcc
	v_lshlrev_b32_e32 v42, 2, v34
	ds_bpermute_b32 v34, v42, v17
	s_waitcnt lgkmcnt(0)
	v_add_f32_e32 v17, v17, v34
	v_xor_b32_e32 v34, 4, v196
	v_cmp_lt_i32_e32 vcc, v34, v27
	s_nop 1
	v_cndmask_b32_e32 v34, v196, v34, vcc
	v_lshlrev_b32_e32 v43, 2, v34
	ds_bpermute_b32 v34, v43, v17
	s_waitcnt lgkmcnt(0)
	v_add_f32_e32 v17, v17, v34
	v_xor_b32_e32 v34, 2, v196
	v_cmp_lt_i32_e32 vcc, v34, v27
	s_nop 1
	v_cndmask_b32_e32 v34, v196, v34, vcc
	v_lshlrev_b32_e32 v44, 2, v34
	ds_bpermute_b32 v34, v44, v17
	s_waitcnt lgkmcnt(0)
	v_add_f32_e32 v17, v17, v34
	v_xor_b32_e32 v34, 1, v196
	v_cmp_lt_i32_e32 vcc, v34, v27
	s_nop 1
	v_cndmask_b32_e32 v27, v196, v34, vcc
	v_lshlrev_b32_e32 v27, 2, v27
	ds_bpermute_b32 v34, v27, v17
	s_waitcnt lgkmcnt(0)
	v_add_f32_e32 v17, v17, v34
	v_fmamk_f32 v13, v17, 0xba800000, v13
	v_fmamk_f32 v12, v17, 0xba800000, v12
	v_fmamk_f32 v15, v17, 0xba800000, v15
	v_fmac_f32_e32 v14, 0xba800000, v17
	v_pk_mul_f32 v[34:35], v[14:15], v[14:15]
	v_pk_mul_f32 v[36:37], v[12:13], v[12:13]
	v_fmamk_f32 v9, v17, 0xba800000, v9
	v_pk_mov_b32 v[38:39], v[36:37], v[34:35] op_sel:[1,0]
	v_mov_b32_e32 v37, v35
	v_pk_add_f32 v[34:35], v[38:39], v[36:37]
	v_fmamk_f32 v8, v17, 0xba800000, v8
	v_fmamk_f32 v11, v17, 0xba800000, v11
	v_fmac_f32_e32 v10, 0xba800000, v17
	v_pk_add_f32 v[34:35], v[34:35], v[34:35] op_sel_hi:[0,1]
	v_pk_mul_f32 v[36:37], v[10:11], v[10:11]
	v_pk_mul_f32 v[38:39], v[8:9], v[8:9]
	v_fmamk_f32 v4, v17, 0xba800000, v4
	v_pk_mov_b32 v[40:41], v[38:39], v[36:37] op_sel:[1,0]
	v_mov_b32_e32 v39, v37
	v_fmamk_f32 v5, v17, 0xba800000, v5
	v_fmac_f32_e32 v6, 0xba800000, v17
	v_mul_f32_e32 v34, v4, v4
	v_pk_add_f32 v[36:37], v[40:41], v[38:39]
	v_fmamk_f32 v7, v17, 0xba800000, v7
	v_pk_fma_f32 v[38:39], v[4:5], v[4:5], v[34:35] op_sel_hi:[1,1,0]
	v_mul_f32_e32 v34, v6, v6
	v_pk_add_f32 v[36:37], v[36:37], v[36:37] op_sel_hi:[0,1]
	v_pk_fma_f32 v[40:41], v[6:7], v[6:7], v[34:35] op_sel_hi:[1,1,0]
	v_fmamk_f32 v3, v17, 0xba800000, v3
	v_fmamk_f32 v2, v17, 0xba800000, v2
	v_fmamk_f32 v1, v17, 0xba800000, v1
	v_fmac_f32_e32 v0, 0xba800000, v17
	v_mul_f32_e32 v38, v0, v0
	v_mul_f32_e32 v40, v1, v1
	v_mul_f32_e32 v34, v2, v2
	v_mul_f32_e32 v36, v3, v3
	v_pk_add_f32 v[38:39], v[38:39], v[40:41]
	v_pk_add_f32 v[34:35], v[34:35], v[36:37]
	s_nop 0
	v_pk_add_f32 v[34:35], v[38:39], v[34:35]
	s_nop 0
	v_add_f32_e32 v17, v34, v35
	ds_bpermute_b32 v29, v29, v17
	s_waitcnt lgkmcnt(0)
	v_add_f32_e32 v17, v17, v29
	ds_bpermute_b32 v29, v31, v17
	s_waitcnt lgkmcnt(0)
	v_add_f32_e32 v17, v17, v29
	ds_bpermute_b32 v29, v42, v17
	s_waitcnt lgkmcnt(0)
	v_add_f32_e32 v17, v17, v29
	ds_bpermute_b32 v29, v43, v17
	s_waitcnt lgkmcnt(0)
	v_add_f32_e32 v17, v17, v29
	ds_bpermute_b32 v29, v44, v17
	s_waitcnt lgkmcnt(0)
	v_add_f32_e32 v17, v17, v29
	ds_bpermute_b32 v27, v27, v17
	s_waitcnt lgkmcnt(0)
	v_add_f32_e32 v17, v17, v27
	v_fmamk_f32 v17, v17, 0x3a800000, v197
	v_cmp_gt_f32_e32 vcc, s18, v17
	v_mul_f32_e32 v27, 0x4b800000, v17
	s_nop 0
	v_cndmask_b32_e32 v17, v17, v27, vcc
	v_rsq_f32_e32 v17, v17
	s_nop 0
	v_mul_f32_e32 v27, 0x45800000, v17
	v_cndmask_b32_e32 v34, v17, v27, vcc
	v_pk_mul_f32 v[12:13], v[12:13], v[34:35] op_sel_hi:[1,0]
	v_pk_mul_f32 v[14:15], v[14:15], v[34:35] op_sel_hi:[1,0]
	v_pk_mul_f32 v[8:9], v[8:9], v[34:35] op_sel_hi:[1,0]
	v_pk_mul_f32 v[10:11], v[10:11], v[34:35] op_sel_hi:[1,0]
	v_pk_mul_f32 v[4:5], v[4:5], v[34:35] op_sel_hi:[1,0]
	v_pk_mul_f32 v[6:7], v[6:7], v[34:35] op_sel_hi:[1,0]
	v_pk_mul_f32 v[0:1], v[0:1], v[34:35] op_sel_hi:[1,0]
	v_pk_mul_f32 v[2:3], v[2:3], v[34:35] op_sel_hi:[1,0]
	s_andn2_b64 vcc, exec, s[60:61]
	v_pk_fma_f32 v[14:15], v[142:143], v[14:15], v[146:147]
	v_pk_fma_f32 v[12:13], v[140:141], v[12:13], v[144:145]
	v_pk_fma_f32 v[10:11], v[150:151], v[10:11], v[154:155]
	v_pk_fma_f32 v[8:9], v[148:149], v[8:9], v[152:153]
	v_pk_fma_f32 v[6:7], v[158:159], v[6:7], v[162:163]
	v_pk_fma_f32 v[4:5], v[156:157], v[4:5], v[160:161]
	v_pk_fma_f32 v[2:3], v[166:167], v[2:3], v[170:171]
	v_pk_fma_f32 v[0:1], v[164:165], v[0:1], v[168:169]
	global_store_dwordx4 v[32:33], v[12:15], off
	global_store_dwordx4 v[32:33], v[8:11], off offset:1024
	global_store_dwordx4 v[32:33], v[4:7], off offset:2048
	global_store_dwordx4 v[32:33], v[0:3], off offset:3072
	s_cbranch_vccnz .LBB0_1486
	v_ashrrev_i32_e32 v17, 31, v16
	s_and_saveexec_b64 s[18:19], s[2:3]
	s_cbranch_execz .LBB0_1485
	v_mov_b32_e32 v34, v177
	v_lshl_add_u64 v[32:33], v[16:17], 3, s[12:13]
	s_nop 0
	v_mov_b32_e32 v35, v34
	global_store_dwordx2 v[32:33], v[34:35], off
	s_branch .LBB0_1485
